# XCD-local barrier release poll: s_sleep 4 instead of 1 (less polling pressure on the release counter line)
# speedup vs baseline: 1.0085x; 1.0048x over previous
.Llb_spin:
	global_load_dword v1, v0, s[4:5] sc1
	s_waitcnt vmcnt(0)
	v_readfirstlane_b32 s9, v1
	s_cmp_ge_u32 s9, s8
	s_cbranch_scc1 .Llb_done
	s_sleep 4
	s_add_i32 s12, s12, 1
	s_cmp_lt_u32 s12, 0x1000
	s_cbranch_scc1 .Llb_spin
